# P1 epilogue stores (q/k/v/silu(z)/pp) use nt policy; plus P0/P3 x loads nt
# baseline (speedup 1.0000x reference)
.LBB0_110:
	v_mov_b32_e32 v133, v136
	s_lshl_b32 s28, s68, 8
	v_readfirstlane_b32 s8, v133
	s_and_b32 s9, s8, 0xc0
	s_ashr_i32 s8, s8, 2
	s_andn2_b32 s8, s8, 63
	s_add_i32 s8, s8, s28
	v_and_or_b32 v132, v133, 15, s8
	s_lshl_b32 s8, s97, 8
	s_or_b32 s8, s9, s8
	v_lshrrev_b32_e32 v133, 1, v133
	v_and_or_b32 v134, v133, 24, s8
	v_ashrrev_i32_e32 v133, 31, v132
	v_ashrrev_i32_e32 v135, 31, v134
	v_lshlrev_b64 v[142:143], 11, v[132:133]
	v_lshl_add_u64 v[142:143], s[14:15], 0, v[142:143]
	v_lshlrev_b64 v[134:135], 1, v[134:135]
	v_lshl_add_u64 v[142:143], v[142:143], 0, v[134:135]
	v_cvt_pk_bf16_f32 v112, v112, v113
	v_cvt_pk_bf16_f32 v113, v114, v115
	v_cvt_pk_bf16_f32 v114, v116, v117
	v_cvt_pk_bf16_f32 v115, v118, v119
	global_store_dwordx4 v[142:143], v[112:115], off nt
	v_cvt_pk_bf16_f32 v88, v88, v89
	v_cvt_pk_bf16_f32 v89, v90, v91
	v_cvt_pk_bf16_f32 v112, v120, v121
	v_cvt_pk_bf16_f32 v113, v122, v123
	v_cvt_pk_bf16_f32 v114, v124, v125
	v_cvt_pk_bf16_f32 v115, v126, v127
	global_store_dwordx4 v[142:143], v[112:115], off offset:64 nt
	v_cvt_pk_bf16_f32 v90, v92, v93
	v_cvt_pk_bf16_f32 v91, v94, v95
	v_or_b32_e32 v112, 16, v132
	v_ashrrev_i32_e32 v113, 31, v112
	v_lshlrev_b64 v[112:113], 11, v[112:113]
	v_lshl_add_u64 v[112:113], s[14:15], 0, v[112:113]
	v_lshl_add_u64 v[112:113], v[112:113], 0, v[134:135]
	global_store_dwordx4 v[112:113], v[88:91], off nt
	v_cvt_pk_bf16_f32 v56, v56, v57
	v_cvt_pk_bf16_f32 v57, v58, v59
	v_cvt_pk_bf16_f32 v88, v104, v105
	v_cvt_pk_bf16_f32 v89, v106, v107
	v_cvt_pk_bf16_f32 v90, v108, v109
	v_cvt_pk_bf16_f32 v91, v110, v111
	global_store_dwordx4 v[112:113], v[88:91], off offset:64 nt
	v_cvt_pk_bf16_f32 v58, v60, v61
	v_cvt_pk_bf16_f32 v59, v62, v63
	v_or_b32_e32 v88, 32, v132
	v_ashrrev_i32_e32 v89, 31, v88
	v_lshlrev_b64 v[88:89], 11, v[88:89]
	v_lshl_add_u64 v[88:89], s[14:15], 0, v[88:89]
	v_lshl_add_u64 v[88:89], v[88:89], 0, v[134:135]
	global_store_dwordx4 v[88:89], v[56:59], off nt
	v_cvt_pk_bf16_f32 v16, v16, v17
	v_cvt_pk_bf16_f32 v17, v18, v19
	v_cvt_pk_bf16_f32 v56, v72, v73
	v_cvt_pk_bf16_f32 v57, v74, v75
	v_cvt_pk_bf16_f32 v58, v76, v77
	v_cvt_pk_bf16_f32 v59, v78, v79
	global_store_dwordx4 v[88:89], v[56:59], off offset:64 nt
	v_cvt_pk_bf16_f32 v18, v20, v21
	v_cvt_pk_bf16_f32 v19, v22, v23
	v_or_b32_e32 v56, 48, v132
	v_ashrrev_i32_e32 v57, 31, v56
	v_lshlrev_b64 v[56:57], 11, v[56:57]
	v_lshl_add_u64 v[56:57], s[14:15], 0, v[56:57]
	v_lshl_add_u64 v[56:57], v[56:57], 0, v[134:135]
	s_mov_b32 s8, 0x40000
	global_store_dwordx4 v[56:57], v[16:19], off nt
	v_add_co_u32_e32 v22, vcc, s8, v142
	s_nop 0
	v_cvt_pk_bf16_f32 v16, v40, v41
	v_cvt_pk_bf16_f32 v17, v42, v43
	v_cvt_pk_bf16_f32 v18, v44, v45
	v_cvt_pk_bf16_f32 v19, v46, v47
	global_store_dwordx4 v[56:57], v[16:19], off offset:64 nt
	s_mov_b64 s[28:29], 0x40000
	v_addc_co_u32_e32 v23, vcc, 0, v143, vcc
	v_cvt_pk_bf16_f32 v16, v80, v81
	v_cvt_pk_bf16_f32 v17, v82, v83
	v_cvt_pk_bf16_f32 v18, v84, v85
	v_cvt_pk_bf16_f32 v19, v86, v87
	v_lshl_add_u64 v[20:21], v[142:143], 0, s[28:29]
	global_store_dwordx4 v[22:23], v[16:19], off nt
	v_add_co_u32_e32 v22, vcc, s94, v142
	s_nop 0
	v_cvt_pk_bf16_f32 v16, v96, v97
	v_cvt_pk_bf16_f32 v17, v98, v99
	v_cvt_pk_bf16_f32 v18, v100, v101
	v_cvt_pk_bf16_f32 v19, v102, v103
	global_store_dwordx4 v[20:21], v[16:19], off offset:64 nt
	v_addc_co_u32_e32 v23, vcc, 0, v143, vcc
	s_nop 0
	v_cvt_pk_bf16_f32 v16, v48, v49
	v_cvt_pk_bf16_f32 v17, v50, v51
	v_cvt_pk_bf16_f32 v18, v52, v53
	v_cvt_pk_bf16_f32 v19, v54, v55
	s_mov_b64 s[28:29], 0x48000
	global_store_dwordx4 v[22:23], v[16:19], off nt
	v_add_co_u32_e32 v22, vcc, s95, v142
	v_lshl_add_u64 v[20:21], v[142:143], 0, s[28:29]
	v_cvt_pk_bf16_f32 v16, v64, v65
	v_cvt_pk_bf16_f32 v17, v66, v67
	v_cvt_pk_bf16_f32 v18, v68, v69
	v_cvt_pk_bf16_f32 v19, v70, v71
	v_addc_co_u32_e32 v23, vcc, 0, v143, vcc
	global_store_dwordx4 v[20:21], v[16:19], off offset:64 nt
	v_cvt_pk_bf16_f32 v0, v0, v1
	v_cvt_pk_bf16_f32 v1, v2, v3
	v_cvt_pk_bf16_f32 v16, v24, v25
	v_cvt_pk_bf16_f32 v17, v26, v27
	v_cvt_pk_bf16_f32 v18, v28, v29
	v_cvt_pk_bf16_f32 v19, v30, v31
	v_cvt_pk_bf16_f32 v2, v4, v5
	v_add_co_u32_e32 v4, vcc, s96, v142
	v_lshl_add_u64 v[20:21], v[142:143], 0, s[60:61]
	global_store_dwordx4 v[22:23], v[16:19], off nt
	v_cvt_pk_bf16_f32 v3, v6, v7
	v_addc_co_u32_e32 v5, vcc, 0, v143, vcc
	v_cvt_pk_bf16_f32 v16, v32, v33
	v_cvt_pk_bf16_f32 v17, v34, v35
	v_cvt_pk_bf16_f32 v18, v36, v37
	v_cvt_pk_bf16_f32 v19, v38, v39
	global_store_dwordx4 v[20:21], v[16:19], off offset:64 nt
	global_store_dwordx4 v[4:5], v[0:3], off nt
	s_andn2_b64 vcc, exec, s[0:1]
	v_lshl_add_u64 v[16:17], v[142:143], 0, s[62:63]
	v_cvt_pk_bf16_f32 v0, v8, v9
	v_cvt_pk_bf16_f32 v1, v10, v11
	v_cvt_pk_bf16_f32 v2, v12, v13
	v_cvt_pk_bf16_f32 v3, v14, v15
	s_mov_b64 s[0:1], -1
	global_store_dwordx4 v[16:17], v[0:3], off offset:64 nt
	s_cbranch_vccnz .LBB0_101
	s_andn2_b64 vcc, exec, s[16:17]
	s_cbranch_vccnz .LBB0_100
	s_barrier
	s_branch .LBB0_100

.LBB0_154:
	s_add_u32 s8, s52, s89
	s_addc_u32 s9, s53, 0
	s_ashr_i32 s5, s4, 31
	s_lshl_b64 s[4:5], s[4:5], 1
	s_add_u32 s4, s8, s4
	s_addc_u32 s5, s9, s5
	v_lshlrev_b32_e32 v148, 4, v158
	v_and_b32_e32 v142, 0x1fcf, v169
	v_lshl_add_u64 v[136:137], s[4:5], 0, v[148:149]
	s_ashr_i32 s4, s59, 13
	s_mul_hi_i32 s5, s68, s4
	s_mul_i32 s4, s68, s4
	v_mul_u32_u24_e32 v140, s66, v142
	v_lshl_add_u64 v[138:139], s[4:5], 1, v[136:137]
	v_lshlrev_b32_e32 v148, 1, v140
	v_lshl_add_u64 v[140:141], v[138:139], 0, v[148:149]
	v_cvt_pk_bf16_f32 v128, v128, v129
	v_cvt_pk_bf16_f32 v129, v130, v131
	v_cvt_pk_bf16_f32 v130, v132, v133
	v_cvt_pk_bf16_f32 v131, v134, v135
	global_store_dwordx4 v[140:141], v[128:131], off nt
	v_mov_b64_e32 v[134:135], v[110:111]
	s_andn2_b64 vcc, exec, s[70:71]
	v_cndmask_b32_e64 v128, 0, 1, s[70:71]
	v_cmp_ne_u32_e64 s[4:5], 1, v128
	v_mov_b64_e32 v[130:131], v[118:119]
	v_mov_b64_e32 v[128:129], v[116:117]
	v_mov_b64_e32 v[132:133], v[108:109]
	s_cbranch_vccnz .LBB0_156
	v_mul_f32_e32 v128, 0xbfb8aa3b, v116
	v_mul_f32_e32 v129, 0xbfb8aa3b, v117
	v_mul_f32_e32 v130, 0xbfb8aa3b, v118
	v_mul_f32_e32 v131, 0xbfb8aa3b, v119
	v_mul_f32_e32 v132, 0xbfb8aa3b, v108
	v_mul_f32_e32 v133, 0xbfb8aa3b, v109
	v_mul_f32_e32 v134, 0xbfb8aa3b, v110
	v_mul_f32_e32 v135, 0xbfb8aa3b, v111
	v_exp_f32_e32 v128, v128
	v_exp_f32_e32 v129, v129
	v_exp_f32_e32 v130, v130
	v_exp_f32_e32 v131, v131
	v_exp_f32_e32 v132, v132
	v_exp_f32_e32 v133, v133
	v_exp_f32_e32 v134, v134
	v_exp_f32_e32 v135, v135
	v_add_f32_e32 v128, 1.0, v128
	v_add_f32_e32 v129, 1.0, v129
	v_add_f32_e32 v130, 1.0, v130
	v_add_f32_e32 v131, 1.0, v131
	v_add_f32_e32 v132, 1.0, v132
	v_add_f32_e32 v133, 1.0, v133
	v_add_f32_e32 v134, 1.0, v134
	v_add_f32_e32 v135, 1.0, v135
	v_rcp_f32_e32 v128, v128
	v_rcp_f32_e32 v129, v129
	v_rcp_f32_e32 v130, v130
	v_rcp_f32_e32 v131, v131
	v_rcp_f32_e32 v132, v132
	v_rcp_f32_e32 v134, v134
	v_rcp_f32_e32 v135, v135
	v_rcp_f32_e32 v133, v133
	v_pk_mul_f32 v[130:131], v[118:119], v[130:131]
	v_pk_mul_f32 v[128:129], v[116:117], v[128:129]
	v_pk_mul_f32 v[134:135], v[110:111], v[134:135]
	v_pk_mul_f32 v[132:133], v[108:109], v[132:133]
.LBB0_156:
	v_cvt_pk_bf16_f32 v128, v128, v129
	v_cvt_pk_bf16_f32 v129, v130, v131
	v_cvt_pk_bf16_f32 v130, v132, v133
	v_cvt_pk_bf16_f32 v131, v134, v135
	global_store_dwordx4 v[140:141], v[128:131], off offset:64 nt
	v_mov_b64_e32 v[134:135], v[106:107]
	s_and_b64 vcc, exec, s[4:5]
	v_mov_b64_e32 v[130:131], v[114:115]
	v_mov_b64_e32 v[128:129], v[112:113]
	v_mov_b64_e32 v[132:133], v[104:105]
	s_cbranch_vccnz .LBB0_158
	v_mul_f32_e32 v128, 0xbfb8aa3b, v112
	v_mul_f32_e32 v129, 0xbfb8aa3b, v113
	v_mul_f32_e32 v130, 0xbfb8aa3b, v114
	v_mul_f32_e32 v131, 0xbfb8aa3b, v115
	v_mul_f32_e32 v132, 0xbfb8aa3b, v104
	v_mul_f32_e32 v133, 0xbfb8aa3b, v105
	v_mul_f32_e32 v134, 0xbfb8aa3b, v106
	v_mul_f32_e32 v135, 0xbfb8aa3b, v107
	v_exp_f32_e32 v128, v128
	v_exp_f32_e32 v129, v129
	v_exp_f32_e32 v130, v130
	v_exp_f32_e32 v131, v131
	v_exp_f32_e32 v132, v132
	v_exp_f32_e32 v133, v133
	v_exp_f32_e32 v134, v134
	v_exp_f32_e32 v135, v135
	v_add_f32_e32 v128, 1.0, v128
	v_add_f32_e32 v129, 1.0, v129
	v_add_f32_e32 v130, 1.0, v130
	v_add_f32_e32 v131, 1.0, v131
	v_add_f32_e32 v132, 1.0, v132
	v_add_f32_e32 v133, 1.0, v133
	v_add_f32_e32 v134, 1.0, v134
	v_add_f32_e32 v135, 1.0, v135
	v_rcp_f32_e32 v128, v128
	v_rcp_f32_e32 v129, v129
	v_rcp_f32_e32 v130, v130
	v_rcp_f32_e32 v131, v131
	v_rcp_f32_e32 v132, v132
	v_rcp_f32_e32 v134, v134
	v_rcp_f32_e32 v135, v135
	v_rcp_f32_e32 v133, v133
	v_pk_mul_f32 v[130:131], v[114:115], v[130:131]
	v_pk_mul_f32 v[128:129], v[112:113], v[128:129]
	v_pk_mul_f32 v[134:135], v[106:107], v[134:135]
	v_pk_mul_f32 v[132:133], v[104:105], v[132:133]
.LBB0_158:
	v_or_b32_e32 v140, 16, v142
	v_mul_u32_u24_e32 v140, s66, v140
	v_lshlrev_b32_e32 v148, 1, v140
	v_lshl_add_u64 v[140:141], v[138:139], 0, v[148:149]
	v_cvt_pk_bf16_f32 v128, v128, v129
	v_cvt_pk_bf16_f32 v129, v130, v131
	v_cvt_pk_bf16_f32 v130, v132, v133
	v_cvt_pk_bf16_f32 v131, v134, v135
	global_store_dwordx4 v[140:141], v[128:131], off nt
	v_mov_b64_e32 v[134:135], v[94:95]
	s_and_b64 vcc, exec, s[4:5]
	v_mov_b64_e32 v[130:131], v[102:103]
	v_mov_b64_e32 v[128:129], v[100:101]
	v_mov_b64_e32 v[132:133], v[92:93]
	s_cbranch_vccnz .LBB0_160
	v_mul_f32_e32 v128, 0xbfb8aa3b, v100
	v_mul_f32_e32 v129, 0xbfb8aa3b, v101
	v_mul_f32_e32 v130, 0xbfb8aa3b, v102
	v_mul_f32_e32 v131, 0xbfb8aa3b, v103
	v_mul_f32_e32 v132, 0xbfb8aa3b, v92
	v_mul_f32_e32 v133, 0xbfb8aa3b, v93
	v_mul_f32_e32 v134, 0xbfb8aa3b, v94
	v_mul_f32_e32 v135, 0xbfb8aa3b, v95
	v_exp_f32_e32 v128, v128
	v_exp_f32_e32 v129, v129
	v_exp_f32_e32 v130, v130
	v_exp_f32_e32 v131, v131
	v_exp_f32_e32 v132, v132
	v_exp_f32_e32 v133, v133
	v_exp_f32_e32 v134, v134
	v_exp_f32_e32 v135, v135
	v_add_f32_e32 v128, 1.0, v128
	v_add_f32_e32 v129, 1.0, v129
	v_add_f32_e32 v130, 1.0, v130
	v_add_f32_e32 v131, 1.0, v131
	v_add_f32_e32 v132, 1.0, v132
	v_add_f32_e32 v133, 1.0, v133
	v_add_f32_e32 v134, 1.0, v134
	v_add_f32_e32 v135, 1.0, v135
	v_rcp_f32_e32 v128, v128
	v_rcp_f32_e32 v129, v129
	v_rcp_f32_e32 v130, v130
	v_rcp_f32_e32 v131, v131
	v_rcp_f32_e32 v132, v132
	v_rcp_f32_e32 v134, v134
	v_rcp_f32_e32 v135, v135
	v_rcp_f32_e32 v133, v133
	v_pk_mul_f32 v[130:131], v[102:103], v[130:131]
	v_pk_mul_f32 v[128:129], v[100:101], v[128:129]
	v_pk_mul_f32 v[134:135], v[94:95], v[134:135]
	v_pk_mul_f32 v[132:133], v[92:93], v[132:133]
.LBB0_160:
	v_cvt_pk_bf16_f32 v128, v128, v129
	v_cvt_pk_bf16_f32 v129, v130, v131
	v_cvt_pk_bf16_f32 v130, v132, v133
	v_cvt_pk_bf16_f32 v131, v134, v135
	global_store_dwordx4 v[140:141], v[128:131], off offset:64 nt
	v_mov_b64_e32 v[134:135], v[90:91]
	s_and_b64 vcc, exec, s[4:5]
	v_mov_b64_e32 v[130:131], v[98:99]
	v_mov_b64_e32 v[128:129], v[96:97]
	v_mov_b64_e32 v[132:133], v[88:89]
	s_cbranch_vccnz .LBB0_162
	v_mul_f32_e32 v128, 0xbfb8aa3b, v96
	v_mul_f32_e32 v129, 0xbfb8aa3b, v97
	v_mul_f32_e32 v130, 0xbfb8aa3b, v98
	v_mul_f32_e32 v131, 0xbfb8aa3b, v99
	v_mul_f32_e32 v132, 0xbfb8aa3b, v88
	v_mul_f32_e32 v133, 0xbfb8aa3b, v89
	v_mul_f32_e32 v134, 0xbfb8aa3b, v90
	v_mul_f32_e32 v135, 0xbfb8aa3b, v91
	v_exp_f32_e32 v128, v128
	v_exp_f32_e32 v129, v129
	v_exp_f32_e32 v130, v130
	v_exp_f32_e32 v131, v131
	v_exp_f32_e32 v132, v132
	v_exp_f32_e32 v133, v133
	v_exp_f32_e32 v134, v134
	v_exp_f32_e32 v135, v135
	v_add_f32_e32 v128, 1.0, v128
	v_add_f32_e32 v129, 1.0, v129
	v_add_f32_e32 v130, 1.0, v130
	v_add_f32_e32 v131, 1.0, v131
	v_add_f32_e32 v132, 1.0, v132
	v_add_f32_e32 v133, 1.0, v133
	v_add_f32_e32 v134, 1.0, v134
	v_add_f32_e32 v135, 1.0, v135
	v_rcp_f32_e32 v128, v128
	v_rcp_f32_e32 v129, v129
	v_rcp_f32_e32 v130, v130
	v_rcp_f32_e32 v131, v131
	v_rcp_f32_e32 v132, v132
	v_rcp_f32_e32 v134, v134
	v_rcp_f32_e32 v135, v135
	v_rcp_f32_e32 v133, v133
	v_pk_mul_f32 v[130:131], v[98:99], v[130:131]
	v_pk_mul_f32 v[128:129], v[96:97], v[128:129]
	v_pk_mul_f32 v[134:135], v[90:91], v[134:135]
	v_pk_mul_f32 v[132:133], v[88:89], v[132:133]
.LBB0_162:
	v_or_b32_e32 v140, 32, v142
	v_mul_u32_u24_e32 v140, s66, v140
	v_lshlrev_b32_e32 v148, 1, v140
	v_lshl_add_u64 v[140:141], v[138:139], 0, v[148:149]
	v_cvt_pk_bf16_f32 v128, v128, v129
	v_cvt_pk_bf16_f32 v129, v130, v131
	v_cvt_pk_bf16_f32 v130, v132, v133
	v_cvt_pk_bf16_f32 v131, v134, v135
	global_store_dwordx4 v[140:141], v[128:131], off nt
	v_mov_b64_e32 v[134:135], v[78:79]
	s_and_b64 vcc, exec, s[4:5]
	v_mov_b64_e32 v[130:131], v[86:87]
	v_mov_b64_e32 v[128:129], v[84:85]
	v_mov_b64_e32 v[132:133], v[76:77]
	s_cbranch_vccnz .LBB0_164
	v_mul_f32_e32 v128, 0xbfb8aa3b, v84
	v_mul_f32_e32 v129, 0xbfb8aa3b, v85
	v_mul_f32_e32 v130, 0xbfb8aa3b, v86
	v_mul_f32_e32 v131, 0xbfb8aa3b, v87
	v_mul_f32_e32 v132, 0xbfb8aa3b, v76
	v_mul_f32_e32 v133, 0xbfb8aa3b, v77
	v_mul_f32_e32 v134, 0xbfb8aa3b, v78
	v_mul_f32_e32 v135, 0xbfb8aa3b, v79
	v_exp_f32_e32 v128, v128
	v_exp_f32_e32 v129, v129
	v_exp_f32_e32 v130, v130
	v_exp_f32_e32 v131, v131
	v_exp_f32_e32 v132, v132
	v_exp_f32_e32 v133, v133
	v_exp_f32_e32 v134, v134
	v_exp_f32_e32 v135, v135
	v_add_f32_e32 v128, 1.0, v128
	v_add_f32_e32 v129, 1.0, v129
	v_add_f32_e32 v130, 1.0, v130
	v_add_f32_e32 v131, 1.0, v131
	v_add_f32_e32 v132, 1.0, v132
	v_add_f32_e32 v133, 1.0, v133
	v_add_f32_e32 v134, 1.0, v134
	v_add_f32_e32 v135, 1.0, v135
	v_rcp_f32_e32 v128, v128
	v_rcp_f32_e32 v129, v129
	v_rcp_f32_e32 v130, v130
	v_rcp_f32_e32 v131, v131
	v_rcp_f32_e32 v132, v132
	v_rcp_f32_e32 v134, v134
	v_rcp_f32_e32 v135, v135
	v_rcp_f32_e32 v133, v133
	v_pk_mul_f32 v[130:131], v[86:87], v[130:131]
	v_pk_mul_f32 v[128:129], v[84:85], v[128:129]
	v_pk_mul_f32 v[134:135], v[78:79], v[134:135]
	v_pk_mul_f32 v[132:133], v[76:77], v[132:133]
.LBB0_164:
	v_cvt_pk_bf16_f32 v128, v128, v129
	v_cvt_pk_bf16_f32 v129, v130, v131
	v_cvt_pk_bf16_f32 v130, v132, v133
	v_cvt_pk_bf16_f32 v131, v134, v135
	global_store_dwordx4 v[140:141], v[128:131], off offset:64 nt
	v_mov_b64_e32 v[134:135], v[74:75]
	s_and_b64 vcc, exec, s[4:5]
	v_mov_b64_e32 v[130:131], v[82:83]
	v_mov_b64_e32 v[128:129], v[80:81]
	v_mov_b64_e32 v[132:133], v[72:73]
	s_cbranch_vccnz .LBB0_166
	v_mul_f32_e32 v128, 0xbfb8aa3b, v80
	v_mul_f32_e32 v129, 0xbfb8aa3b, v81
	v_mul_f32_e32 v130, 0xbfb8aa3b, v82
	v_mul_f32_e32 v131, 0xbfb8aa3b, v83
	v_mul_f32_e32 v132, 0xbfb8aa3b, v72
	v_mul_f32_e32 v133, 0xbfb8aa3b, v73
	v_mul_f32_e32 v134, 0xbfb8aa3b, v74
	v_mul_f32_e32 v135, 0xbfb8aa3b, v75
	v_exp_f32_e32 v128, v128
	v_exp_f32_e32 v129, v129
	v_exp_f32_e32 v130, v130
	v_exp_f32_e32 v131, v131
	v_exp_f32_e32 v132, v132
	v_exp_f32_e32 v133, v133
	v_exp_f32_e32 v134, v134
	v_exp_f32_e32 v135, v135
	v_add_f32_e32 v128, 1.0, v128
	v_add_f32_e32 v129, 1.0, v129
	v_add_f32_e32 v130, 1.0, v130
	v_add_f32_e32 v131, 1.0, v131
	v_add_f32_e32 v132, 1.0, v132
	v_add_f32_e32 v133, 1.0, v133
	v_add_f32_e32 v134, 1.0, v134
	v_add_f32_e32 v135, 1.0, v135
	v_rcp_f32_e32 v128, v128
	v_rcp_f32_e32 v129, v129
	v_rcp_f32_e32 v130, v130
	v_rcp_f32_e32 v131, v131
	v_rcp_f32_e32 v132, v132
	v_rcp_f32_e32 v134, v134
	v_rcp_f32_e32 v135, v135
	v_rcp_f32_e32 v133, v133
	v_pk_mul_f32 v[130:131], v[82:83], v[130:131]
	v_pk_mul_f32 v[128:129], v[80:81], v[128:129]
	v_pk_mul_f32 v[134:135], v[74:75], v[134:135]
	v_pk_mul_f32 v[132:133], v[72:73], v[132:133]
.LBB0_166:
	v_or_b32_e32 v140, 48, v142
	v_mul_u32_u24_e32 v140, s66, v140
	v_lshlrev_b32_e32 v148, 1, v140
	v_lshl_add_u64 v[138:139], v[138:139], 0, v[148:149]
	v_cvt_pk_bf16_f32 v128, v128, v129
	v_cvt_pk_bf16_f32 v129, v130, v131
	v_cvt_pk_bf16_f32 v130, v132, v133
	v_cvt_pk_bf16_f32 v131, v134, v135
	global_store_dwordx4 v[138:139], v[128:131], off nt
	v_mov_b64_e32 v[134:135], v[66:67]
	s_and_b64 vcc, exec, s[4:5]
	v_mov_b64_e32 v[130:131], v[70:71]
	v_mov_b64_e32 v[128:129], v[68:69]
	v_mov_b64_e32 v[132:133], v[64:65]
	s_cbranch_vccnz .LBB0_168
	v_mul_f32_e32 v128, 0xbfb8aa3b, v68
	v_mul_f32_e32 v129, 0xbfb8aa3b, v69
	v_mul_f32_e32 v130, 0xbfb8aa3b, v70
	v_mul_f32_e32 v131, 0xbfb8aa3b, v71
	v_mul_f32_e32 v132, 0xbfb8aa3b, v64
	v_mul_f32_e32 v133, 0xbfb8aa3b, v65
	v_mul_f32_e32 v134, 0xbfb8aa3b, v66
	v_mul_f32_e32 v135, 0xbfb8aa3b, v67
	v_exp_f32_e32 v128, v128
	v_exp_f32_e32 v129, v129
	v_exp_f32_e32 v130, v130
	v_exp_f32_e32 v131, v131
	v_exp_f32_e32 v132, v132
	v_exp_f32_e32 v133, v133
	v_exp_f32_e32 v134, v134
	v_exp_f32_e32 v135, v135
	v_add_f32_e32 v128, 1.0, v128
	v_add_f32_e32 v129, 1.0, v129
	v_add_f32_e32 v130, 1.0, v130
	v_add_f32_e32 v131, 1.0, v131
	v_add_f32_e32 v132, 1.0, v132
	v_add_f32_e32 v133, 1.0, v133
	v_add_f32_e32 v134, 1.0, v134
	v_add_f32_e32 v135, 1.0, v135
	v_rcp_f32_e32 v128, v128
	v_rcp_f32_e32 v129, v129
	v_rcp_f32_e32 v130, v130
	v_rcp_f32_e32 v131, v131
	v_rcp_f32_e32 v132, v132
	v_rcp_f32_e32 v134, v134
	v_rcp_f32_e32 v135, v135
	v_rcp_f32_e32 v133, v133
	v_pk_mul_f32 v[130:131], v[70:71], v[130:131]
	v_pk_mul_f32 v[128:129], v[68:69], v[128:129]
	v_pk_mul_f32 v[134:135], v[66:67], v[134:135]
	v_pk_mul_f32 v[132:133], v[64:65], v[132:133]
.LBB0_168:
	v_cvt_pk_bf16_f32 v128, v128, v129
	v_cvt_pk_bf16_f32 v129, v130, v131
	v_cvt_pk_bf16_f32 v130, v132, v133
	v_cvt_pk_bf16_f32 v131, v134, v135
	global_store_dwordx4 v[138:139], v[128:131], off offset:64 nt
	v_mov_b64_e32 v[134:135], v[58:59]
	s_and_b64 vcc, exec, s[4:5]
	v_mov_b64_e32 v[130:131], v[62:63]
	v_mov_b64_e32 v[128:129], v[60:61]
	v_mov_b64_e32 v[132:133], v[56:57]
	s_cbranch_vccnz .LBB0_170
	v_mul_f32_e32 v128, 0xbfb8aa3b, v60
	v_mul_f32_e32 v129, 0xbfb8aa3b, v61
	v_mul_f32_e32 v130, 0xbfb8aa3b, v62
	v_mul_f32_e32 v131, 0xbfb8aa3b, v63
	v_mul_f32_e32 v132, 0xbfb8aa3b, v56
	v_mul_f32_e32 v133, 0xbfb8aa3b, v57
	v_mul_f32_e32 v134, 0xbfb8aa3b, v58
	v_mul_f32_e32 v135, 0xbfb8aa3b, v59
	v_exp_f32_e32 v128, v128
	v_exp_f32_e32 v129, v129
	v_exp_f32_e32 v130, v130
	v_exp_f32_e32 v131, v131
	v_exp_f32_e32 v132, v132
	v_exp_f32_e32 v133, v133
	v_exp_f32_e32 v134, v134
	v_exp_f32_e32 v135, v135
	v_add_f32_e32 v128, 1.0, v128
	v_add_f32_e32 v129, 1.0, v129
	v_add_f32_e32 v130, 1.0, v130
	v_add_f32_e32 v131, 1.0, v131
	v_add_f32_e32 v132, 1.0, v132
	v_add_f32_e32 v133, 1.0, v133
	v_add_f32_e32 v134, 1.0, v134
	v_add_f32_e32 v135, 1.0, v135
	v_rcp_f32_e32 v128, v128
	v_rcp_f32_e32 v129, v129
	v_rcp_f32_e32 v130, v130
	v_rcp_f32_e32 v131, v131
	v_rcp_f32_e32 v132, v132
	v_rcp_f32_e32 v134, v134
	v_rcp_f32_e32 v135, v135
	v_rcp_f32_e32 v133, v133
	v_pk_mul_f32 v[130:131], v[62:63], v[130:131]
	v_pk_mul_f32 v[128:129], v[60:61], v[128:129]
	v_pk_mul_f32 v[134:135], v[58:59], v[134:135]
	v_pk_mul_f32 v[132:133], v[56:57], v[132:133]
.LBB0_170:
	v_add_u32_e32 v138, 0x80, v169
	v_and_b32_e32 v140, 0x1fcf, v138
	v_ashrrev_i32_e32 v138, 13, v138
	v_mad_i64_i32 v[138:139], s[28:29], s68, v138, 0
	v_lshl_add_u64 v[136:137], v[138:139], 1, v[136:137]
	v_mul_u32_u24_e32 v138, s66, v140
	v_lshlrev_b32_e32 v148, 1, v138
	v_lshl_add_u64 v[138:139], v[136:137], 0, v[148:149]
	v_cvt_pk_bf16_f32 v128, v128, v129
	v_cvt_pk_bf16_f32 v129, v130, v131
	v_cvt_pk_bf16_f32 v130, v132, v133
	v_cvt_pk_bf16_f32 v131, v134, v135
	global_store_dwordx4 v[138:139], v[128:131], off nt
	v_mov_b64_e32 v[134:135], v[46:47]
	s_and_b64 vcc, exec, s[4:5]
	v_mov_b64_e32 v[130:131], v[54:55]
	v_mov_b64_e32 v[128:129], v[52:53]
	v_mov_b64_e32 v[132:133], v[44:45]
	s_cbranch_vccnz .LBB0_172
	v_mul_f32_e32 v128, 0xbfb8aa3b, v52
	v_mul_f32_e32 v129, 0xbfb8aa3b, v53
	v_mul_f32_e32 v130, 0xbfb8aa3b, v54
	v_mul_f32_e32 v131, 0xbfb8aa3b, v55
	v_mul_f32_e32 v132, 0xbfb8aa3b, v44
	v_mul_f32_e32 v133, 0xbfb8aa3b, v45
	v_mul_f32_e32 v134, 0xbfb8aa3b, v46
	v_mul_f32_e32 v135, 0xbfb8aa3b, v47
	v_exp_f32_e32 v128, v128
	v_exp_f32_e32 v129, v129
	v_exp_f32_e32 v130, v130
	v_exp_f32_e32 v131, v131
	v_exp_f32_e32 v132, v132
	v_exp_f32_e32 v133, v133
	v_exp_f32_e32 v134, v134
	v_exp_f32_e32 v135, v135
	v_add_f32_e32 v128, 1.0, v128
	v_add_f32_e32 v129, 1.0, v129
	v_add_f32_e32 v130, 1.0, v130
	v_add_f32_e32 v131, 1.0, v131
	v_add_f32_e32 v132, 1.0, v132
	v_add_f32_e32 v133, 1.0, v133
	v_add_f32_e32 v134, 1.0, v134
	v_add_f32_e32 v135, 1.0, v135
	v_rcp_f32_e32 v128, v128
	v_rcp_f32_e32 v129, v129
	v_rcp_f32_e32 v130, v130
	v_rcp_f32_e32 v131, v131
	v_rcp_f32_e32 v132, v132
	v_rcp_f32_e32 v134, v134
	v_rcp_f32_e32 v135, v135
	v_rcp_f32_e32 v133, v133
	v_pk_mul_f32 v[130:131], v[54:55], v[130:131]
	v_pk_mul_f32 v[128:129], v[52:53], v[128:129]
	v_pk_mul_f32 v[134:135], v[46:47], v[134:135]
	v_pk_mul_f32 v[132:133], v[44:45], v[132:133]
.LBB0_172:
	v_cvt_pk_bf16_f32 v128, v128, v129
	v_cvt_pk_bf16_f32 v129, v130, v131
	v_cvt_pk_bf16_f32 v130, v132, v133
	v_cvt_pk_bf16_f32 v131, v134, v135
	global_store_dwordx4 v[138:139], v[128:131], off offset:64 nt
	v_mov_b64_e32 v[134:135], v[42:43]
	s_and_b64 vcc, exec, s[4:5]
	v_mov_b64_e32 v[130:131], v[50:51]
	v_mov_b64_e32 v[128:129], v[48:49]
	v_mov_b64_e32 v[132:133], v[40:41]
	s_cbranch_vccnz .LBB0_174
	v_mul_f32_e32 v128, 0xbfb8aa3b, v48
	v_mul_f32_e32 v129, 0xbfb8aa3b, v49
	v_mul_f32_e32 v130, 0xbfb8aa3b, v50
	v_mul_f32_e32 v131, 0xbfb8aa3b, v51
	v_mul_f32_e32 v132, 0xbfb8aa3b, v40
	v_mul_f32_e32 v133, 0xbfb8aa3b, v41
	v_mul_f32_e32 v134, 0xbfb8aa3b, v42
	v_mul_f32_e32 v135, 0xbfb8aa3b, v43
	v_exp_f32_e32 v128, v128
	v_exp_f32_e32 v129, v129
	v_exp_f32_e32 v130, v130
	v_exp_f32_e32 v131, v131
	v_exp_f32_e32 v132, v132
	v_exp_f32_e32 v133, v133
	v_exp_f32_e32 v134, v134
	v_exp_f32_e32 v135, v135
	v_add_f32_e32 v128, 1.0, v128
	v_add_f32_e32 v129, 1.0, v129
	v_add_f32_e32 v130, 1.0, v130
	v_add_f32_e32 v131, 1.0, v131
	v_add_f32_e32 v132, 1.0, v132
	v_add_f32_e32 v133, 1.0, v133
	v_add_f32_e32 v134, 1.0, v134
	v_add_f32_e32 v135, 1.0, v135
	v_rcp_f32_e32 v128, v128
	v_rcp_f32_e32 v129, v129
	v_rcp_f32_e32 v130, v130
	v_rcp_f32_e32 v131, v131
	v_rcp_f32_e32 v132, v132
	v_rcp_f32_e32 v134, v134
	v_rcp_f32_e32 v135, v135
	v_rcp_f32_e32 v133, v133
	v_pk_mul_f32 v[130:131], v[50:51], v[130:131]
	v_pk_mul_f32 v[128:129], v[48:49], v[128:129]
	v_pk_mul_f32 v[134:135], v[42:43], v[134:135]
	v_pk_mul_f32 v[132:133], v[40:41], v[132:133]
.LBB0_174:
	v_or_b32_e32 v138, 16, v140
	v_mul_u32_u24_e32 v138, s66, v138
	v_lshlrev_b32_e32 v148, 1, v138
	v_lshl_add_u64 v[138:139], v[136:137], 0, v[148:149]
	v_cvt_pk_bf16_f32 v128, v128, v129
	v_cvt_pk_bf16_f32 v129, v130, v131
	v_cvt_pk_bf16_f32 v130, v132, v133
	v_cvt_pk_bf16_f32 v131, v134, v135
	global_store_dwordx4 v[138:139], v[128:131], off nt
	v_mov_b64_e32 v[134:135], v[30:31]
	s_and_b64 vcc, exec, s[4:5]
	v_mov_b64_e32 v[130:131], v[38:39]
	v_mov_b64_e32 v[128:129], v[36:37]
	v_mov_b64_e32 v[132:133], v[28:29]
	s_cbranch_vccnz .LBB0_176
	v_mul_f32_e32 v128, 0xbfb8aa3b, v36
	v_mul_f32_e32 v129, 0xbfb8aa3b, v37
	v_mul_f32_e32 v130, 0xbfb8aa3b, v38
	v_mul_f32_e32 v131, 0xbfb8aa3b, v39
	v_mul_f32_e32 v132, 0xbfb8aa3b, v28
	v_mul_f32_e32 v133, 0xbfb8aa3b, v29
	v_mul_f32_e32 v134, 0xbfb8aa3b, v30
	v_mul_f32_e32 v135, 0xbfb8aa3b, v31
	v_exp_f32_e32 v128, v128
	v_exp_f32_e32 v129, v129
	v_exp_f32_e32 v130, v130
	v_exp_f32_e32 v131, v131
	v_exp_f32_e32 v132, v132
	v_exp_f32_e32 v133, v133
	v_exp_f32_e32 v134, v134
	v_exp_f32_e32 v135, v135
	v_add_f32_e32 v128, 1.0, v128
	v_add_f32_e32 v129, 1.0, v129
	v_add_f32_e32 v130, 1.0, v130
	v_add_f32_e32 v131, 1.0, v131
	v_add_f32_e32 v132, 1.0, v132
	v_add_f32_e32 v133, 1.0, v133
	v_add_f32_e32 v134, 1.0, v134
	v_add_f32_e32 v135, 1.0, v135
	v_rcp_f32_e32 v128, v128
	v_rcp_f32_e32 v129, v129
	v_rcp_f32_e32 v130, v130
	v_rcp_f32_e32 v131, v131
	v_rcp_f32_e32 v132, v132
	v_rcp_f32_e32 v134, v134
	v_rcp_f32_e32 v135, v135
	v_rcp_f32_e32 v133, v133
	v_pk_mul_f32 v[130:131], v[38:39], v[130:131]
	v_pk_mul_f32 v[128:129], v[36:37], v[128:129]
	v_pk_mul_f32 v[134:135], v[30:31], v[134:135]
	v_pk_mul_f32 v[132:133], v[28:29], v[132:133]
.LBB0_176:
	v_cvt_pk_bf16_f32 v128, v128, v129
	v_cvt_pk_bf16_f32 v129, v130, v131
	v_cvt_pk_bf16_f32 v130, v132, v133
	v_cvt_pk_bf16_f32 v131, v134, v135
	global_store_dwordx4 v[138:139], v[128:131], off offset:64 nt
	v_mov_b64_e32 v[134:135], v[26:27]
	s_and_b64 vcc, exec, s[4:5]
	v_mov_b64_e32 v[130:131], v[34:35]
	v_mov_b64_e32 v[128:129], v[32:33]
	v_mov_b64_e32 v[132:133], v[24:25]
	s_cbranch_vccnz .LBB0_178
	v_mul_f32_e32 v128, 0xbfb8aa3b, v32
	v_mul_f32_e32 v129, 0xbfb8aa3b, v33
	v_mul_f32_e32 v130, 0xbfb8aa3b, v34
	v_mul_f32_e32 v131, 0xbfb8aa3b, v35
	v_mul_f32_e32 v132, 0xbfb8aa3b, v24
	v_mul_f32_e32 v133, 0xbfb8aa3b, v25
	v_mul_f32_e32 v134, 0xbfb8aa3b, v26
	v_mul_f32_e32 v135, 0xbfb8aa3b, v27
	v_exp_f32_e32 v128, v128
	v_exp_f32_e32 v129, v129
	v_exp_f32_e32 v130, v130
	v_exp_f32_e32 v131, v131
	v_exp_f32_e32 v132, v132
	v_exp_f32_e32 v133, v133
	v_exp_f32_e32 v134, v134
	v_exp_f32_e32 v135, v135
	v_add_f32_e32 v128, 1.0, v128
	v_add_f32_e32 v129, 1.0, v129
	v_add_f32_e32 v130, 1.0, v130
	v_add_f32_e32 v131, 1.0, v131
	v_add_f32_e32 v132, 1.0, v132
	v_add_f32_e32 v133, 1.0, v133
	v_add_f32_e32 v134, 1.0, v134
	v_add_f32_e32 v135, 1.0, v135
	v_rcp_f32_e32 v128, v128
	v_rcp_f32_e32 v129, v129
	v_rcp_f32_e32 v130, v130
	v_rcp_f32_e32 v131, v131
	v_rcp_f32_e32 v132, v132
	v_rcp_f32_e32 v134, v134
	v_rcp_f32_e32 v135, v135
	v_rcp_f32_e32 v133, v133
	v_pk_mul_f32 v[130:131], v[34:35], v[130:131]
	v_pk_mul_f32 v[128:129], v[32:33], v[128:129]
	v_pk_mul_f32 v[134:135], v[26:27], v[134:135]
	v_pk_mul_f32 v[132:133], v[24:25], v[132:133]
.LBB0_178:
	v_or_b32_e32 v138, 32, v140
	v_mul_u32_u24_e32 v138, s66, v138
	v_lshlrev_b32_e32 v148, 1, v138
	v_lshl_add_u64 v[138:139], v[136:137], 0, v[148:149]
	v_cvt_pk_bf16_f32 v128, v128, v129
	v_cvt_pk_bf16_f32 v129, v130, v131
	v_cvt_pk_bf16_f32 v130, v132, v133
	v_cvt_pk_bf16_f32 v131, v134, v135
	global_store_dwordx4 v[138:139], v[128:131], off nt
	v_mov_b64_e32 v[134:135], v[14:15]
	s_and_b64 vcc, exec, s[4:5]
	v_mov_b64_e32 v[130:131], v[22:23]
	v_mov_b64_e32 v[128:129], v[20:21]
	v_mov_b64_e32 v[132:133], v[12:13]
	s_cbranch_vccnz .LBB0_180
	v_mul_f32_e32 v128, 0xbfb8aa3b, v20
	v_mul_f32_e32 v129, 0xbfb8aa3b, v21
	v_mul_f32_e32 v130, 0xbfb8aa3b, v22
	v_mul_f32_e32 v131, 0xbfb8aa3b, v23
	v_mul_f32_e32 v132, 0xbfb8aa3b, v12
	v_mul_f32_e32 v133, 0xbfb8aa3b, v13
	v_mul_f32_e32 v134, 0xbfb8aa3b, v14
	v_mul_f32_e32 v135, 0xbfb8aa3b, v15
	v_exp_f32_e32 v128, v128
	v_exp_f32_e32 v129, v129
	v_exp_f32_e32 v130, v130
	v_exp_f32_e32 v131, v131
	v_exp_f32_e32 v132, v132
	v_exp_f32_e32 v133, v133
	v_exp_f32_e32 v134, v134
	v_exp_f32_e32 v135, v135
	v_add_f32_e32 v128, 1.0, v128
	v_add_f32_e32 v129, 1.0, v129
	v_add_f32_e32 v130, 1.0, v130
	v_add_f32_e32 v131, 1.0, v131
	v_add_f32_e32 v132, 1.0, v132
	v_add_f32_e32 v133, 1.0, v133
	v_add_f32_e32 v134, 1.0, v134
	v_add_f32_e32 v135, 1.0, v135
	v_rcp_f32_e32 v128, v128
	v_rcp_f32_e32 v129, v129
	v_rcp_f32_e32 v130, v130
	v_rcp_f32_e32 v131, v131
	v_rcp_f32_e32 v132, v132
	v_rcp_f32_e32 v134, v134
	v_rcp_f32_e32 v135, v135
	v_rcp_f32_e32 v133, v133
	v_pk_mul_f32 v[130:131], v[22:23], v[130:131]
	v_pk_mul_f32 v[128:129], v[20:21], v[128:129]
	v_pk_mul_f32 v[134:135], v[14:15], v[134:135]
	v_pk_mul_f32 v[132:133], v[12:13], v[132:133]
.LBB0_180:
	v_cvt_pk_bf16_f32 v128, v128, v129
	v_cvt_pk_bf16_f32 v129, v130, v131
	v_cvt_pk_bf16_f32 v130, v132, v133
	v_cvt_pk_bf16_f32 v131, v134, v135
	global_store_dwordx4 v[138:139], v[128:131], off offset:64 nt
	v_mov_b64_e32 v[134:135], v[10:11]
	s_and_b64 vcc, exec, s[4:5]
	v_mov_b64_e32 v[130:131], v[18:19]
	v_mov_b64_e32 v[128:129], v[16:17]
	v_mov_b64_e32 v[132:133], v[8:9]
	s_cbranch_vccnz .LBB0_182
	v_mul_f32_e32 v128, 0xbfb8aa3b, v16
	v_mul_f32_e32 v129, 0xbfb8aa3b, v17
	v_mul_f32_e32 v130, 0xbfb8aa3b, v18
	v_mul_f32_e32 v131, 0xbfb8aa3b, v19
	v_mul_f32_e32 v132, 0xbfb8aa3b, v8
	v_mul_f32_e32 v133, 0xbfb8aa3b, v9
	v_mul_f32_e32 v134, 0xbfb8aa3b, v10
	v_mul_f32_e32 v135, 0xbfb8aa3b, v11
	v_exp_f32_e32 v128, v128
	v_exp_f32_e32 v129, v129
	v_exp_f32_e32 v130, v130
	v_exp_f32_e32 v131, v131
	v_exp_f32_e32 v132, v132
	v_exp_f32_e32 v133, v133
	v_exp_f32_e32 v134, v134
	v_exp_f32_e32 v135, v135
	v_add_f32_e32 v128, 1.0, v128
	v_add_f32_e32 v129, 1.0, v129
	v_add_f32_e32 v130, 1.0, v130
	v_add_f32_e32 v131, 1.0, v131
	v_add_f32_e32 v132, 1.0, v132
	v_add_f32_e32 v133, 1.0, v133
	v_add_f32_e32 v134, 1.0, v134
	v_add_f32_e32 v135, 1.0, v135
	v_rcp_f32_e32 v128, v128
	v_rcp_f32_e32 v129, v129
	v_rcp_f32_e32 v130, v130
	v_rcp_f32_e32 v131, v131
	v_rcp_f32_e32 v132, v132
	v_rcp_f32_e32 v134, v134
	v_rcp_f32_e32 v135, v135
	v_rcp_f32_e32 v133, v133
	v_pk_mul_f32 v[130:131], v[18:19], v[130:131]
	v_pk_mul_f32 v[128:129], v[16:17], v[128:129]
	v_pk_mul_f32 v[134:135], v[10:11], v[134:135]
	v_pk_mul_f32 v[132:133], v[8:9], v[132:133]
.LBB0_182:
	v_or_b32_e32 v138, 48, v140
	v_mul_u32_u24_e32 v138, s66, v138
	v_lshlrev_b32_e32 v148, 1, v138
	v_lshl_add_u64 v[136:137], v[136:137], 0, v[148:149]
	v_cvt_pk_bf16_f32 v128, v128, v129
	v_cvt_pk_bf16_f32 v129, v130, v131
	v_cvt_pk_bf16_f32 v130, v132, v133
	v_cvt_pk_bf16_f32 v131, v134, v135
	global_store_dwordx4 v[136:137], v[128:131], off nt
	v_mov_b64_e32 v[134:135], v[2:3]
	s_and_b64 vcc, exec, s[4:5]
	v_mov_b64_e32 v[130:131], v[6:7]
	v_mov_b64_e32 v[128:129], v[4:5]
	v_mov_b64_e32 v[132:133], v[0:1]
	s_cbranch_vccnz .LBB0_184
	v_mul_f32_e32 v128, 0xbfb8aa3b, v4
	v_mul_f32_e32 v129, 0xbfb8aa3b, v5
	v_mul_f32_e32 v130, 0xbfb8aa3b, v6
	v_mul_f32_e32 v131, 0xbfb8aa3b, v7
	v_mul_f32_e32 v132, 0xbfb8aa3b, v0
	v_mul_f32_e32 v133, 0xbfb8aa3b, v1
	v_mul_f32_e32 v134, 0xbfb8aa3b, v2
	v_mul_f32_e32 v135, 0xbfb8aa3b, v3
	v_exp_f32_e32 v128, v128
	v_exp_f32_e32 v129, v129
	v_exp_f32_e32 v130, v130
	v_exp_f32_e32 v131, v131
	v_exp_f32_e32 v132, v132
	v_exp_f32_e32 v133, v133
	v_exp_f32_e32 v134, v134
	v_exp_f32_e32 v135, v135
	v_add_f32_e32 v128, 1.0, v128
	v_add_f32_e32 v129, 1.0, v129
	v_add_f32_e32 v130, 1.0, v130
	v_add_f32_e32 v131, 1.0, v131
	v_add_f32_e32 v132, 1.0, v132
	v_add_f32_e32 v133, 1.0, v133
	v_add_f32_e32 v134, 1.0, v134
	v_add_f32_e32 v135, 1.0, v135
	v_rcp_f32_e32 v128, v128
	v_rcp_f32_e32 v129, v129
	v_rcp_f32_e32 v130, v130
	v_rcp_f32_e32 v131, v131
	v_rcp_f32_e32 v132, v132
	v_rcp_f32_e32 v134, v134
	v_rcp_f32_e32 v135, v135
	v_rcp_f32_e32 v133, v133
	v_pk_mul_f32 v[130:131], v[6:7], v[130:131]
	v_pk_mul_f32 v[128:129], v[4:5], v[128:129]
	v_pk_mul_f32 v[134:135], v[2:3], v[134:135]
	v_pk_mul_f32 v[132:133], v[0:1], v[132:133]
.LBB0_184:
	v_cvt_pk_bf16_f32 v128, v128, v129
	v_cvt_pk_bf16_f32 v129, v130, v131
	v_cvt_pk_bf16_f32 v130, v132, v133
	v_cvt_pk_bf16_f32 v131, v134, v135
	global_store_dwordx4 v[136:137], v[128:131], off offset:64 nt
	s_mov_b64 s[4:5], 0
.LBB0_185:
	s_and_b64 vcc, exec, s[4:5]
	s_cbranch_vccz .LBB0_187
	s_cmp_gt_i32 s88, 1
	s_cselect_b64 s[4:5], -1, 0
	s_cmp_lg_u64 s[4:5], 0
	s_subb_u32 s4, s88, 0
	s_lshl_b32 s4, s4, 6
	s_ashr_i32 s5, s4, 31
	s_lshl_b64 s[4:5], s[4:5], 2
	s_add_u32 s28, s76, s4
	s_addc_u32 s29, s77, s5
	v_lshlrev_b32_e32 v132, 5, v158
	global_load_dwordx4 v[136:139], v132, s[28:29] offset:16
	global_load_dwordx4 v[140:143], v132, s[28:29]
	global_load_dwordx4 v[128:131], v132, s[28:29] offset:144
	s_nop 0
	global_load_dwordx4 v[132:135], v132, s[28:29] offset:128
	v_mov_b32_e32 v172, v125
	v_mov_b32_e32 v173, v117
	v_mov_b32_e32 v160, v124
	v_mov_b32_e32 v161, v116
	v_pk_mul_f32 v[172:173], v[172:173], v[172:173]
	v_mov_b32_e32 v174, v127
	v_mov_b32_e32 v175, v119
	v_pk_fma_f32 v[160:161], v[160:161], v[160:161], v[172:173]
	v_mov_b32_e32 v172, v126
	v_mov_b32_e32 v173, v118
	v_pk_mul_f32 v[174:175], v[174:175], v[174:175]
	v_mov_b32_e32 v176, v123
	v_pk_fma_f32 v[172:173], v[172:173], v[172:173], v[174:175]
	v_mov_b32_e32 v174, v121
	v_mov_b32_e32 v175, v109
	v_pk_add_f32 v[160:161], v[160:161], v[172:173]
	v_mov_b32_e32 v172, v120
	v_mov_b32_e32 v173, v108
	v_pk_mul_f32 v[174:175], v[174:175], v[174:175]
	v_mov_b32_e32 v177, v111
	v_pk_fma_f32 v[172:173], v[172:173], v[172:173], v[174:175]
	v_mov_b32_e32 v174, v122
	v_mov_b32_e32 v175, v110
	v_pk_mul_f32 v[176:177], v[176:177], v[176:177]
	v_mov_b32_e32 v178, v107
	v_pk_fma_f32 v[174:175], v[174:175], v[174:175], v[176:177]
	v_mov_b32_e32 v176, v115
	v_pk_add_f32 v[172:173], v[172:173], v[174:175]
	v_mov_b32_e32 v174, v113
	v_mov_b32_e32 v175, v101
	v_pk_add_f32 v[160:161], v[160:161], v[172:173]
	v_mov_b32_e32 v172, v112
	v_mov_b32_e32 v173, v100
	v_pk_mul_f32 v[174:175], v[174:175], v[174:175]
	v_mov_b32_e32 v177, v103
	v_pk_fma_f32 v[172:173], v[172:173], v[172:173], v[174:175]
	v_mov_b32_e32 v174, v114
	v_mov_b32_e32 v175, v102
	v_pk_mul_f32 v[176:177], v[176:177], v[176:177]
	v_mov_b32_e32 v179, v95
	v_pk_fma_f32 v[174:175], v[174:175], v[174:175], v[176:177]
	v_mov_b32_e32 v176, v105
	v_mov_b32_e32 v177, v93
	v_pk_add_f32 v[172:173], v[172:173], v[174:175]
	v_mov_b32_e32 v174, v104
	v_mov_b32_e32 v175, v92
	v_pk_mul_f32 v[176:177], v[176:177], v[176:177]
	v_pk_mul_f32 v[178:179], v[178:179], v[178:179]
	v_pk_fma_f32 v[174:175], v[174:175], v[174:175], v[176:177]
	v_mov_b32_e32 v176, v106
	v_mov_b32_e32 v177, v94
	v_and_b32_e32 v159, 64, v168
	v_pk_fma_f32 v[176:177], v[176:177], v[176:177], v[178:179]
	v_xor_b32_e32 v148, 16, v168
	v_add_u32_e32 v159, 64, v159
	v_pk_add_f32 v[174:175], v[174:175], v[176:177]
	v_cmp_lt_i32_e32 vcc, v148, v159
	v_pk_add_f32 v[172:173], v[172:173], v[174:175]
	v_mov_b32_e32 v175, v160
	v_cndmask_b32_e32 v148, v168, v148, vcc
	v_mov_b32_e32 v174, v172
	v_mov_b32_e32 v160, v173
	v_lshlrev_b32_e32 v171, 2, v148
	v_pk_add_f32 v[172:173], v[174:175], v[160:161]
	ds_bpermute_b32 v175, v171, v173
	ds_bpermute_b32 v174, v171, v172
	v_xor_b32_e32 v148, 32, v168
	v_cmp_lt_i32_e32 vcc, v148, v159
	s_cmp_eq_u32 s88, 3
	s_cselect_b32 s4, s85, 0x7800000
	v_cndmask_b32_e32 v148, v168, v148, vcc
	v_lshlrev_b32_e32 v170, 2, v148
	v_lshlrev_b32_e32 v148, 4, v158
	s_waitcnt lgkmcnt(0)
	v_pk_add_f32 v[158:159], v[172:173], v[174:175]
	ds_bpermute_b32 v173, v170, v159
	ds_bpermute_b32 v172, v170, v158
	s_cmp_lg_u32 s88, 1
	s_cselect_b32 s8, s4, 0x4800000
	s_and_b64 s[4:5], exec, s[64:65]
	s_cselect_b32 s4, 0x3800000, s8
	s_add_u32 s4, s52, s4
	s_waitcnt lgkmcnt(0)
	v_pk_add_f32 v[172:173], v[158:159], v[172:173]
	v_mov_b64_e32 v[158:159], s[50:51]
	s_addc_u32 s5, s53, 0
	v_pk_fma_f32 v[172:173], v[172:173], s[48:49], v[158:159] op_sel_hi:[1,0,0]
	v_lshl_add_u64 v[160:161], s[4:5], 0, v[148:149]
	s_ashr_i32 s4, s59, 10
	v_mul_f32_e32 v148, 0x4b800000, v173
	v_cmp_gt_f32_e32 vcc, s86, v173
	s_and_b32 s8, s57, 7
	s_and_b32 s4, s4, -8
	v_cndmask_b32_e32 v148, v173, v148, vcc
	s_or_b32 s4, s4, s8
	v_rsq_f32_e32 v162, v148
	s_ashr_i32 s5, s4, 31
	s_lshl_b64 s[4:5], s[4:5], 20
	v_lshlrev_b32_e32 v148, 7, v169
	v_lshl_add_u64 v[174:175], v[160:161], 0, s[4:5]
	v_and_b32_e32 v148, 0xfe780, v148
	v_lshl_add_u64 v[174:175], v[174:175], 0, v[148:149]
	v_mul_f32_e32 v148, 0x45800000, v162
	v_cndmask_b32_e32 v148, v162, v148, vcc
	v_pk_mul_f32 v[124:125], v[124:125], v[148:149] op_sel_hi:[1,0]
	v_pk_mul_f32 v[126:127], v[126:127], v[148:149] op_sel_hi:[1,0]
	v_pk_mul_f32 v[120:121], v[120:121], v[148:149] op_sel_hi:[1,0]
	v_pk_mul_f32 v[122:123], v[122:123], v[148:149] op_sel_hi:[1,0]
	s_waitcnt vmcnt(0)
	v_pk_mul_f32 v[126:127], v[142:143], v[126:127]
	v_pk_mul_f32 v[124:125], v[140:141], v[124:125]
	v_pk_mul_f32 v[176:177], v[138:139], v[122:123]
	v_pk_mul_f32 v[122:123], v[136:137], v[120:121]
	v_pk_mul_f32 v[116:117], v[116:117], v[148:149] op_sel_hi:[1,0]
	v_cvt_pk_bf16_f32 v120, v124, v125
	v_cvt_pk_bf16_f32 v121, v126, v127
	v_cvt_pk_bf16_f32 v122, v122, v123
	v_cvt_pk_bf16_f32 v123, v176, v177
	v_pk_mul_f32 v[116:117], v[132:133], v[116:117]
	v_pk_mul_f32 v[108:109], v[108:109], v[148:149] op_sel_hi:[1,0]
	v_pk_mul_f32 v[110:111], v[110:111], v[148:149] op_sel_hi:[1,0]
	global_store_dwordx4 v[174:175], v[120:123], off nt
	v_cmp_gt_f32_e32 vcc, s86, v172
	v_pk_mul_f32 v[118:119], v[118:119], v[148:149] op_sel_hi:[1,0]
	v_pk_mul_f32 v[120:121], v[130:131], v[110:111]
	v_pk_mul_f32 v[110:111], v[128:129], v[108:109]
	v_cvt_pk_bf16_f32 v108, v116, v117
	v_mul_f32_e32 v116, 0x4b800000, v172
	v_cndmask_b32_e32 v116, v172, v116, vcc
	v_rsq_f32_e32 v116, v116
	v_pk_mul_f32 v[118:119], v[134:135], v[118:119]
	v_cvt_pk_bf16_f32 v110, v110, v111
	v_cvt_pk_bf16_f32 v109, v118, v119
	v_cvt_pk_bf16_f32 v111, v120, v121
	global_store_dwordx4 v[174:175], v[108:111], off offset:64 nt
	s_nop 1
	v_mul_f32_e32 v108, 0x45800000, v116
	v_cndmask_b32_e32 v108, v116, v108, vcc
	v_pk_mul_f32 v[110:111], v[112:113], v[108:109] op_sel_hi:[1,0]
	v_pk_mul_f32 v[112:113], v[114:115], v[108:109] op_sel_hi:[1,0]
	v_pk_mul_f32 v[104:105], v[104:105], v[108:109] op_sel_hi:[1,0]
	v_pk_mul_f32 v[106:107], v[106:107], v[108:109] op_sel_hi:[1,0]
	v_pk_mul_f32 v[112:113], v[142:143], v[112:113]
	v_pk_mul_f32 v[110:111], v[140:141], v[110:111]
	v_pk_mul_f32 v[114:115], v[138:139], v[106:107]
	v_pk_mul_f32 v[106:107], v[136:137], v[104:105]
	v_cvt_pk_bf16_f32 v104, v110, v111
	v_cvt_pk_bf16_f32 v105, v112, v113
	v_cvt_pk_bf16_f32 v106, v106, v107
	v_cvt_pk_bf16_f32 v107, v114, v115
	global_store_dwordx4 v[174:175], v[104:107], off offset:2048 nt
	v_mov_b32_e32 v110, v99
	v_mov_b32_e32 v111, v87
	v_mov_b32_e32 v106, v97
	v_mov_b32_e32 v107, v85
	v_mov_b32_e32 v104, v96
	v_mov_b32_e32 v105, v84
	v_pk_mul_f32 v[106:107], v[106:107], v[106:107]
	v_pk_mul_f32 v[110:111], v[110:111], v[110:111]
	v_pk_fma_f32 v[104:105], v[104:105], v[104:105], v[106:107]
	v_mov_b32_e32 v106, v98
	v_mov_b32_e32 v107, v86
	v_pk_fma_f32 v[106:107], v[106:107], v[106:107], v[110:111]
	v_mov_b32_e32 v110, v89
	v_mov_b32_e32 v111, v77
	v_pk_add_f32 v[104:105], v[104:105], v[106:107]
	v_mov_b32_e32 v106, v88
	v_mov_b32_e32 v107, v76
	v_pk_mul_f32 v[110:111], v[110:111], v[110:111]
	v_mov_b32_e32 v112, v91
	v_mov_b32_e32 v113, v79
	v_pk_fma_f32 v[106:107], v[106:107], v[106:107], v[110:111]
	v_mov_b32_e32 v110, v90
	v_mov_b32_e32 v111, v78
	v_pk_mul_f32 v[112:113], v[112:113], v[112:113]
	v_mov_b32_e32 v114, v75
	v_pk_fma_f32 v[110:111], v[110:111], v[110:111], v[112:113]
	v_mov_b32_e32 v112, v83
	v_pk_add_f32 v[106:107], v[106:107], v[110:111]
	v_mov_b32_e32 v110, v81
	v_mov_b32_e32 v111, v69
	v_pk_add_f32 v[104:105], v[104:105], v[106:107]
	v_mov_b32_e32 v106, v80
	v_mov_b32_e32 v107, v68
	v_pk_mul_f32 v[110:111], v[110:111], v[110:111]
	v_mov_b32_e32 v113, v71
	v_pk_fma_f32 v[106:107], v[106:107], v[106:107], v[110:111]
	v_mov_b32_e32 v110, v82
	v_mov_b32_e32 v111, v70
	v_pk_mul_f32 v[112:113], v[112:113], v[112:113]
	v_mov_b32_e32 v115, v67
	v_pk_fma_f32 v[110:111], v[110:111], v[110:111], v[112:113]
	v_mov_b32_e32 v112, v73
	v_mov_b32_e32 v113, v65
	v_pk_add_f32 v[106:107], v[106:107], v[110:111]
	v_mov_b32_e32 v110, v72
	v_mov_b32_e32 v111, v64
	v_pk_mul_f32 v[112:113], v[112:113], v[112:113]
	v_pk_mul_f32 v[114:115], v[114:115], v[114:115]
	v_pk_fma_f32 v[110:111], v[110:111], v[110:111], v[112:113]
	v_mov_b32_e32 v112, v74
	v_mov_b32_e32 v113, v66
	v_pk_fma_f32 v[112:113], v[112:113], v[112:113], v[114:115]
	v_pk_mul_f32 v[100:101], v[100:101], v[108:109] op_sel_hi:[1,0]
	v_pk_add_f32 v[110:111], v[110:111], v[112:113]
	v_pk_mul_f32 v[100:101], v[132:133], v[100:101]
	v_pk_add_f32 v[106:107], v[106:107], v[110:111]
	v_mov_b32_e32 v111, v104
	v_mov_b32_e32 v110, v106
	v_mov_b32_e32 v104, v107
	v_pk_add_f32 v[104:105], v[110:111], v[104:105]
	ds_bpermute_b32 v107, v171, v105
	ds_bpermute_b32 v106, v171, v104
	v_pk_mul_f32 v[92:93], v[92:93], v[108:109] op_sel_hi:[1,0]
	v_pk_mul_f32 v[94:95], v[94:95], v[108:109] op_sel_hi:[1,0]
	v_pk_mul_f32 v[102:103], v[102:103], v[108:109] op_sel_hi:[1,0]
	v_pk_mul_f32 v[108:109], v[130:131], v[94:95]
	s_waitcnt lgkmcnt(0)
	v_pk_add_f32 v[104:105], v[104:105], v[106:107]
	ds_bpermute_b32 v107, v170, v105
	ds_bpermute_b32 v106, v170, v104
	v_pk_mul_f32 v[94:95], v[128:129], v[92:93]
	v_cvt_pk_bf16_f32 v92, v100, v101
	v_pk_mul_f32 v[102:103], v[134:135], v[102:103]
	v_cvt_pk_bf16_f32 v94, v94, v95
	s_waitcnt lgkmcnt(0)
	v_pk_add_f32 v[100:101], v[104:105], v[106:107]
	v_cvt_pk_bf16_f32 v93, v102, v103
	v_pk_fma_f32 v[100:101], v[100:101], s[48:49], v[158:159] op_sel_hi:[1,0,0]
	v_cvt_pk_bf16_f32 v95, v108, v109
	v_mul_f32_e32 v102, 0x4b800000, v101
	v_cmp_gt_f32_e32 vcc, s86, v101
	global_store_dwordx4 v[174:175], v[92:95], off offset:2112 nt
	s_nop 0
	v_cndmask_b32_e32 v101, v101, v102, vcc
	v_rsq_f32_e32 v101, v101
	s_nop 0
	v_mul_f32_e32 v92, 0x45800000, v101
	v_cndmask_b32_e32 v92, v101, v92, vcc
	v_pk_mul_f32 v[94:95], v[96:97], v[92:93] op_sel_hi:[1,0]
	v_pk_mul_f32 v[96:97], v[98:99], v[92:93] op_sel_hi:[1,0]
	v_pk_mul_f32 v[94:95], v[140:141], v[94:95]
	v_pk_mul_f32 v[88:89], v[88:89], v[92:93] op_sel_hi:[1,0]
	v_pk_mul_f32 v[90:91], v[90:91], v[92:93] op_sel_hi:[1,0]
	v_pk_mul_f32 v[96:97], v[142:143], v[96:97]
	v_pk_mul_f32 v[98:99], v[138:139], v[90:91]
	v_pk_mul_f32 v[90:91], v[136:137], v[88:89]
	v_cvt_pk_bf16_f32 v88, v94, v95
	v_add_co_u32_e32 v94, vcc, s87, v174
	v_pk_mul_f32 v[84:85], v[84:85], v[92:93] op_sel_hi:[1,0]
	v_cvt_pk_bf16_f32 v89, v96, v97
	v_cvt_pk_bf16_f32 v90, v90, v91
	v_cvt_pk_bf16_f32 v91, v98, v99
	v_addc_co_u32_e32 v95, vcc, 0, v175, vcc
	v_pk_mul_f32 v[84:85], v[132:133], v[84:85]
	v_pk_mul_f32 v[76:77], v[76:77], v[92:93] op_sel_hi:[1,0]
	v_pk_mul_f32 v[78:79], v[78:79], v[92:93] op_sel_hi:[1,0]
	global_store_dwordx4 v[94:95], v[88:91], off nt
	v_cmp_gt_f32_e32 vcc, s86, v100
	v_pk_mul_f32 v[86:87], v[86:87], v[92:93] op_sel_hi:[1,0]
	v_pk_mul_f32 v[88:89], v[130:131], v[78:79]
	v_pk_mul_f32 v[78:79], v[128:129], v[76:77]
	v_cvt_pk_bf16_f32 v76, v84, v85
	v_mul_f32_e32 v84, 0x4b800000, v100
	v_cndmask_b32_e32 v84, v100, v84, vcc
	v_rsq_f32_e32 v84, v84
	v_pk_mul_f32 v[86:87], v[134:135], v[86:87]
	v_cvt_pk_bf16_f32 v78, v78, v79
	v_cvt_pk_bf16_f32 v77, v86, v87
	v_cvt_pk_bf16_f32 v79, v88, v89
	global_store_dwordx4 v[94:95], v[76:79], off offset:64 nt
	s_nop 1
	v_mul_f32_e32 v76, 0x45800000, v84
	v_cndmask_b32_e32 v76, v84, v76, vcc
	v_pk_mul_f32 v[78:79], v[80:81], v[76:77] op_sel_hi:[1,0]
	v_pk_mul_f32 v[80:81], v[82:83], v[76:77] op_sel_hi:[1,0]
	v_pk_mul_f32 v[72:73], v[72:73], v[76:77] op_sel_hi:[1,0]
	v_pk_mul_f32 v[74:75], v[74:75], v[76:77] op_sel_hi:[1,0]
	v_pk_mul_f32 v[80:81], v[142:143], v[80:81]
	v_pk_mul_f32 v[78:79], v[140:141], v[78:79]
	v_pk_mul_f32 v[82:83], v[138:139], v[74:75]
	v_pk_mul_f32 v[74:75], v[136:137], v[72:73]
	v_pk_mul_f32 v[70:71], v[70:71], v[76:77] op_sel_hi:[1,0]
	v_cvt_pk_bf16_f32 v72, v78, v79
	v_cvt_pk_bf16_f32 v73, v80, v81
	v_cvt_pk_bf16_f32 v74, v74, v75
	v_cvt_pk_bf16_f32 v75, v82, v83
	v_pk_mul_f32 v[68:69], v[68:69], v[76:77] op_sel_hi:[1,0]
	v_pk_mul_f32 v[70:71], v[134:135], v[70:71]
	v_pk_mul_f32 v[64:65], v[64:65], v[76:77] op_sel_hi:[1,0]
	v_pk_mul_f32 v[66:67], v[66:67], v[76:77] op_sel_hi:[1,0]
	global_store_dwordx4 v[94:95], v[72:75], off offset:2048 nt
	v_pk_mul_f32 v[68:69], v[132:133], v[68:69]
	v_mov_b32_e32 v76, v59
	v_pk_mul_f32 v[72:73], v[130:131], v[66:67]
	v_pk_mul_f32 v[66:67], v[128:129], v[64:65]
	v_cvt_pk_bf16_f32 v65, v70, v71
	v_mov_b32_e32 v70, v61
	v_mov_b32_e32 v71, v53
	v_cvt_pk_bf16_f32 v64, v68, v69
	v_mov_b32_e32 v68, v60
	v_mov_b32_e32 v69, v52
	v_pk_mul_f32 v[70:71], v[70:71], v[70:71]
	v_mov_b32_e32 v74, v63
	v_mov_b32_e32 v75, v55
	v_pk_fma_f32 v[68:69], v[68:69], v[68:69], v[70:71]
	v_mov_b32_e32 v70, v62
	v_mov_b32_e32 v71, v54
	v_pk_mul_f32 v[74:75], v[74:75], v[74:75]
	v_mov_b32_e32 v77, v47
	v_pk_fma_f32 v[70:71], v[70:71], v[70:71], v[74:75]
	v_mov_b32_e32 v74, v57
	v_mov_b32_e32 v75, v45
	v_pk_add_f32 v[68:69], v[68:69], v[70:71]
	v_mov_b32_e32 v70, v56
	v_mov_b32_e32 v71, v44
	v_pk_mul_f32 v[74:75], v[74:75], v[74:75]
	v_pk_mul_f32 v[76:77], v[76:77], v[76:77]
	v_pk_fma_f32 v[70:71], v[70:71], v[70:71], v[74:75]
	v_mov_b32_e32 v74, v58
	v_mov_b32_e32 v75, v46
	v_pk_fma_f32 v[74:75], v[74:75], v[74:75], v[76:77]
	v_mov_b32_e32 v76, v51
	v_pk_add_f32 v[70:71], v[70:71], v[74:75]
	v_mov_b32_e32 v74, v49
	v_mov_b32_e32 v75, v37
	v_pk_add_f32 v[68:69], v[68:69], v[70:71]
	v_mov_b32_e32 v70, v48
	v_mov_b32_e32 v71, v36
	v_pk_mul_f32 v[74:75], v[74:75], v[74:75]
	v_mov_b32_e32 v77, v39
	v_pk_fma_f32 v[70:71], v[70:71], v[70:71], v[74:75]
	v_mov_b32_e32 v74, v50
	v_mov_b32_e32 v75, v38
	v_pk_mul_f32 v[76:77], v[76:77], v[76:77]
	v_mov_b32_e32 v78, v43
	v_pk_fma_f32 v[74:75], v[74:75], v[74:75], v[76:77]
	v_mov_b32_e32 v76, v41
	v_mov_b32_e32 v77, v29
	v_pk_add_f32 v[70:71], v[70:71], v[74:75]
	v_mov_b32_e32 v74, v40
	v_mov_b32_e32 v75, v28
	v_pk_mul_f32 v[76:77], v[76:77], v[76:77]
	v_mov_b32_e32 v79, v31
	v_pk_fma_f32 v[74:75], v[74:75], v[74:75], v[76:77]
	v_mov_b32_e32 v76, v42
	v_mov_b32_e32 v77, v30
	v_pk_mul_f32 v[78:79], v[78:79], v[78:79]
	v_cvt_pk_bf16_f32 v66, v66, v67
	v_pk_fma_f32 v[76:77], v[76:77], v[76:77], v[78:79]
	v_cvt_pk_bf16_f32 v67, v72, v73
	v_pk_add_f32 v[74:75], v[74:75], v[76:77]
	global_store_dwordx4 v[94:95], v[64:67], off offset:2112 nt
	v_pk_add_f32 v[70:71], v[70:71], v[74:75]
	v_mov_b32_e32 v75, v68
	v_mov_b32_e32 v74, v70
	v_mov_b32_e32 v68, v71
	v_pk_add_f32 v[68:69], v[74:75], v[68:69]
	ds_bpermute_b32 v71, v171, v69
	ds_bpermute_b32 v70, v171, v68
	v_add_u32_e32 v72, 0x80, v169
	v_ashrrev_i32_e32 v73, 10, v72
	s_waitcnt lgkmcnt(0)
	v_pk_add_f32 v[64:65], v[68:69], v[70:71]
	ds_bpermute_b32 v67, v170, v65
	ds_bpermute_b32 v66, v170, v64
	v_bfi_b32 v68, -8, v73, s57
	v_ashrrev_i32_e32 v69, 31, v68
	v_lshlrev_b64 v[68:69], 20, v[68:69]
	v_lshl_add_u64 v[68:69], v[160:161], 0, v[68:69]
	s_waitcnt lgkmcnt(0)
	v_pk_add_f32 v[64:65], v[64:65], v[66:67]
	s_nop 0
	v_pk_fma_f32 v[64:65], v[64:65], s[48:49], v[158:159] op_sel_hi:[1,0,0]
	s_nop 0
	v_mul_f32_e32 v66, 0x4b800000, v65
	v_cmp_gt_f32_e32 vcc, s86, v65
	s_nop 1
	v_cndmask_b32_e32 v65, v65, v66, vcc
	v_rsq_f32_e32 v65, v65
	v_lshlrev_b32_e32 v66, 7, v72
	v_and_b32_e32 v148, 0xfe780, v66
	v_lshl_add_u64 v[66:67], v[68:69], 0, v[148:149]
	v_mul_f32_e32 v68, 0x45800000, v65
	v_cndmask_b32_e32 v68, v65, v68, vcc
	v_pk_mul_f32 v[60:61], v[60:61], v[68:69] op_sel_hi:[1,0]
	v_pk_mul_f32 v[62:63], v[62:63], v[68:69] op_sel_hi:[1,0]
	v_pk_mul_f32 v[56:57], v[56:57], v[68:69] op_sel_hi:[1,0]
	v_pk_mul_f32 v[58:59], v[58:59], v[68:69] op_sel_hi:[1,0]
	v_pk_mul_f32 v[62:63], v[142:143], v[62:63]
	v_pk_mul_f32 v[60:61], v[140:141], v[60:61]
	v_pk_mul_f32 v[70:71], v[138:139], v[58:59]
	v_pk_mul_f32 v[58:59], v[136:137], v[56:57]
	v_pk_mul_f32 v[52:53], v[52:53], v[68:69] op_sel_hi:[1,0]
	v_cvt_pk_bf16_f32 v56, v60, v61
	v_cvt_pk_bf16_f32 v57, v62, v63
	v_cvt_pk_bf16_f32 v58, v58, v59
	v_cvt_pk_bf16_f32 v59, v70, v71
	v_pk_mul_f32 v[52:53], v[132:133], v[52:53]
	v_pk_mul_f32 v[44:45], v[44:45], v[68:69] op_sel_hi:[1,0]
	v_pk_mul_f32 v[46:47], v[46:47], v[68:69] op_sel_hi:[1,0]
	global_store_dwordx4 v[66:67], v[56:59], off nt
	v_cmp_gt_f32_e32 vcc, s86, v64
	v_pk_mul_f32 v[54:55], v[54:55], v[68:69] op_sel_hi:[1,0]
	v_pk_mul_f32 v[56:57], v[130:131], v[46:47]
	v_pk_mul_f32 v[46:47], v[128:129], v[44:45]
	v_cvt_pk_bf16_f32 v44, v52, v53
	v_mul_f32_e32 v52, 0x4b800000, v64
	v_cndmask_b32_e32 v52, v64, v52, vcc
	v_rsq_f32_e32 v52, v52
	v_pk_mul_f32 v[54:55], v[134:135], v[54:55]
	v_cvt_pk_bf16_f32 v46, v46, v47
	v_cvt_pk_bf16_f32 v45, v54, v55
	v_cvt_pk_bf16_f32 v47, v56, v57
	global_store_dwordx4 v[66:67], v[44:47], off offset:64 nt
	s_nop 1
	v_mul_f32_e32 v44, 0x45800000, v52
	v_cndmask_b32_e32 v44, v52, v44, vcc
	v_pk_mul_f32 v[46:47], v[48:49], v[44:45] op_sel_hi:[1,0]
	v_pk_mul_f32 v[48:49], v[50:51], v[44:45] op_sel_hi:[1,0]
	v_pk_mul_f32 v[40:41], v[40:41], v[44:45] op_sel_hi:[1,0]
	v_pk_mul_f32 v[42:43], v[42:43], v[44:45] op_sel_hi:[1,0]
	v_pk_mul_f32 v[48:49], v[142:143], v[48:49]
	v_pk_mul_f32 v[46:47], v[140:141], v[46:47]
	v_pk_mul_f32 v[50:51], v[138:139], v[42:43]
	v_pk_mul_f32 v[42:43], v[136:137], v[40:41]
	v_cvt_pk_bf16_f32 v40, v46, v47
	v_cvt_pk_bf16_f32 v41, v48, v49
	v_cvt_pk_bf16_f32 v42, v42, v43
	v_cvt_pk_bf16_f32 v43, v50, v51
	global_store_dwordx4 v[66:67], v[40:43], off offset:2048 nt
	v_mov_b32_e32 v46, v35
	v_mov_b32_e32 v47, v23
	v_mov_b32_e32 v42, v33
	v_mov_b32_e32 v43, v21
	v_mov_b32_e32 v40, v32
	v_mov_b32_e32 v41, v20
	v_pk_mul_f32 v[42:43], v[42:43], v[42:43]
	v_pk_mul_f32 v[46:47], v[46:47], v[46:47]
	v_pk_fma_f32 v[40:41], v[40:41], v[40:41], v[42:43]
	v_mov_b32_e32 v42, v34
	v_mov_b32_e32 v43, v22
	v_pk_fma_f32 v[42:43], v[42:43], v[42:43], v[46:47]
	v_mov_b32_e32 v46, v25
	v_mov_b32_e32 v47, v13
	v_pk_add_f32 v[40:41], v[40:41], v[42:43]
	v_mov_b32_e32 v42, v24
	v_mov_b32_e32 v43, v12
	v_pk_mul_f32 v[46:47], v[46:47], v[46:47]
	v_mov_b32_e32 v48, v27
	v_mov_b32_e32 v49, v15
	v_pk_fma_f32 v[42:43], v[42:43], v[42:43], v[46:47]
	v_mov_b32_e32 v46, v26
	v_mov_b32_e32 v47, v14
	v_pk_mul_f32 v[48:49], v[48:49], v[48:49]
	v_mov_b32_e32 v50, v11
	v_pk_fma_f32 v[46:47], v[46:47], v[46:47], v[48:49]
	v_mov_b32_e32 v48, v19
	v_pk_add_f32 v[42:43], v[42:43], v[46:47]
	v_mov_b32_e32 v46, v17
	v_mov_b32_e32 v47, v5
	v_pk_add_f32 v[40:41], v[40:41], v[42:43]
	v_mov_b32_e32 v42, v16
	v_mov_b32_e32 v43, v4
	v_pk_mul_f32 v[46:47], v[46:47], v[46:47]
	v_mov_b32_e32 v49, v7
	v_pk_fma_f32 v[42:43], v[42:43], v[42:43], v[46:47]
	v_mov_b32_e32 v46, v18
	v_mov_b32_e32 v47, v6
	v_pk_mul_f32 v[48:49], v[48:49], v[48:49]
	v_mov_b32_e32 v51, v3
	v_pk_fma_f32 v[46:47], v[46:47], v[46:47], v[48:49]
	v_mov_b32_e32 v48, v9
	v_mov_b32_e32 v49, v1
	v_pk_add_f32 v[42:43], v[42:43], v[46:47]
	v_mov_b32_e32 v46, v8
	v_mov_b32_e32 v47, v0
	v_pk_mul_f32 v[48:49], v[48:49], v[48:49]
	v_pk_mul_f32 v[50:51], v[50:51], v[50:51]
	v_pk_fma_f32 v[46:47], v[46:47], v[46:47], v[48:49]
	v_mov_b32_e32 v48, v10
	v_mov_b32_e32 v49, v2
	v_pk_fma_f32 v[48:49], v[48:49], v[48:49], v[50:51]
	v_pk_mul_f32 v[36:37], v[36:37], v[44:45] op_sel_hi:[1,0]
	v_pk_add_f32 v[46:47], v[46:47], v[48:49]
	v_pk_mul_f32 v[36:37], v[132:133], v[36:37]
	v_pk_add_f32 v[42:43], v[42:43], v[46:47]
	v_mov_b32_e32 v47, v40
	v_mov_b32_e32 v46, v42
	v_mov_b32_e32 v40, v43
	v_pk_add_f32 v[40:41], v[46:47], v[40:41]
	ds_bpermute_b32 v43, v171, v41
	ds_bpermute_b32 v42, v171, v40
	v_pk_mul_f32 v[28:29], v[28:29], v[44:45] op_sel_hi:[1,0]
	v_pk_mul_f32 v[30:31], v[30:31], v[44:45] op_sel_hi:[1,0]
	v_pk_mul_f32 v[38:39], v[38:39], v[44:45] op_sel_hi:[1,0]
	v_pk_mul_f32 v[44:45], v[130:131], v[30:31]
	s_waitcnt lgkmcnt(0)
	v_pk_add_f32 v[40:41], v[40:41], v[42:43]
	ds_bpermute_b32 v43, v170, v41
	ds_bpermute_b32 v42, v170, v40
	v_pk_mul_f32 v[30:31], v[128:129], v[28:29]
	v_cvt_pk_bf16_f32 v28, v36, v37
	v_pk_mul_f32 v[38:39], v[134:135], v[38:39]
	v_cvt_pk_bf16_f32 v30, v30, v31
	s_waitcnt lgkmcnt(0)
	v_pk_add_f32 v[36:37], v[40:41], v[42:43]
	v_cvt_pk_bf16_f32 v29, v38, v39
	v_pk_fma_f32 v[36:37], v[36:37], s[48:49], v[158:159] op_sel_hi:[1,0,0]
	v_cvt_pk_bf16_f32 v31, v44, v45
	v_mul_f32_e32 v38, 0x4b800000, v37
	v_cmp_gt_f32_e32 vcc, s86, v37
	global_store_dwordx4 v[66:67], v[28:31], off offset:2112 nt
	s_nop 0
	v_cndmask_b32_e32 v37, v37, v38, vcc
	v_rsq_f32_e32 v37, v37
	s_nop 0
	v_mul_f32_e32 v28, 0x45800000, v37
	v_cndmask_b32_e32 v28, v37, v28, vcc
	v_pk_mul_f32 v[30:31], v[32:33], v[28:29] op_sel_hi:[1,0]
	v_pk_mul_f32 v[32:33], v[34:35], v[28:29] op_sel_hi:[1,0]
	v_pk_mul_f32 v[30:31], v[140:141], v[30:31]
	v_pk_mul_f32 v[24:25], v[24:25], v[28:29] op_sel_hi:[1,0]
	v_pk_mul_f32 v[26:27], v[26:27], v[28:29] op_sel_hi:[1,0]
	v_pk_mul_f32 v[32:33], v[142:143], v[32:33]
	v_pk_mul_f32 v[34:35], v[138:139], v[26:27]
	v_pk_mul_f32 v[26:27], v[136:137], v[24:25]
	v_cvt_pk_bf16_f32 v24, v30, v31
	v_add_co_u32_e32 v30, vcc, s87, v66
	v_pk_mul_f32 v[20:21], v[20:21], v[28:29] op_sel_hi:[1,0]
	v_cvt_pk_bf16_f32 v25, v32, v33
	v_cvt_pk_bf16_f32 v26, v26, v27
	v_cvt_pk_bf16_f32 v27, v34, v35
	v_addc_co_u32_e32 v31, vcc, 0, v67, vcc
	v_pk_mul_f32 v[20:21], v[132:133], v[20:21]
	v_pk_mul_f32 v[12:13], v[12:13], v[28:29] op_sel_hi:[1,0]
	v_pk_mul_f32 v[14:15], v[14:15], v[28:29] op_sel_hi:[1,0]
	global_store_dwordx4 v[30:31], v[24:27], off nt
	v_cmp_gt_f32_e32 vcc, s86, v36
	v_pk_mul_f32 v[22:23], v[22:23], v[28:29] op_sel_hi:[1,0]
	v_pk_mul_f32 v[24:25], v[130:131], v[14:15]
	v_pk_mul_f32 v[14:15], v[128:129], v[12:13]
	v_cvt_pk_bf16_f32 v12, v20, v21
	v_mul_f32_e32 v20, 0x4b800000, v36
	v_cndmask_b32_e32 v20, v36, v20, vcc
	v_rsq_f32_e32 v20, v20
	v_pk_mul_f32 v[22:23], v[134:135], v[22:23]
	v_cvt_pk_bf16_f32 v14, v14, v15
	v_cvt_pk_bf16_f32 v13, v22, v23
	v_cvt_pk_bf16_f32 v15, v24, v25
	global_store_dwordx4 v[30:31], v[12:15], off offset:64 nt
	s_nop 1
	v_mul_f32_e32 v12, 0x45800000, v20
	v_cndmask_b32_e32 v12, v20, v12, vcc
	v_pk_mul_f32 v[14:15], v[16:17], v[12:13] op_sel_hi:[1,0]
	v_pk_mul_f32 v[16:17], v[18:19], v[12:13] op_sel_hi:[1,0]
	v_pk_mul_f32 v[8:9], v[8:9], v[12:13] op_sel_hi:[1,0]
	v_pk_mul_f32 v[10:11], v[10:11], v[12:13] op_sel_hi:[1,0]
	v_pk_mul_f32 v[16:17], v[142:143], v[16:17]
	v_pk_mul_f32 v[14:15], v[140:141], v[14:15]
	v_pk_mul_f32 v[18:19], v[138:139], v[10:11]
	v_pk_mul_f32 v[10:11], v[136:137], v[8:9]
	v_cvt_pk_bf16_f32 v8, v14, v15
	v_cvt_pk_bf16_f32 v9, v16, v17
	v_cvt_pk_bf16_f32 v10, v10, v11
	v_cvt_pk_bf16_f32 v11, v18, v19
	v_pk_mul_f32 v[4:5], v[4:5], v[12:13] op_sel_hi:[1,0]
	v_pk_mul_f32 v[6:7], v[6:7], v[12:13] op_sel_hi:[1,0]
	v_pk_mul_f32 v[0:1], v[0:1], v[12:13] op_sel_hi:[1,0]
	v_pk_mul_f32 v[2:3], v[2:3], v[12:13] op_sel_hi:[1,0]
	global_store_dwordx4 v[30:31], v[8:11], off offset:2048 nt
	v_pk_mul_f32 v[6:7], v[134:135], v[6:7]
	v_pk_mul_f32 v[4:5], v[132:133], v[4:5]
	v_pk_mul_f32 v[8:9], v[130:131], v[2:3]
	v_pk_mul_f32 v[2:3], v[128:129], v[0:1]
	v_cvt_pk_bf16_f32 v0, v4, v5
	v_cvt_pk_bf16_f32 v1, v6, v7
	v_cvt_pk_bf16_f32 v2, v2, v3
	v_cvt_pk_bf16_f32 v3, v8, v9
	global_store_dwordx4 v[30:31], v[0:3], off offset:2112 nt
